# v093 with the deferred layer-1 FFN weight conversion split 10752 items (gate/up L0 tail) / 6144 items (down L0 tail) instead of 9408 / 7488
# baseline (speedup 1.0000x reference)
; #define LAS __attribute__((address_space(3)))
;     const int nblk = N / 32, items = (K / 64) * nblk;
;     if (it >= items) { it -= items; return false; }
;     const int kb = it / nblk, nb = it % nblk, n0 = 32 * nb;
;     const int drow0 = mode == 0 ? n0 : ((n0 >> 7) * 256 + (mode == 2 ? 128 : 0) + (n0 & 127));
;     transpose_item(W, K, N, WT, 64 * kb, n0, drow0, scr, lane, wsc);
;     return true;
; }
; __device__ __forceinline__ void p0_weights(KAP a, LAS unsigned char* lds, int gw, int NGW, int wave, int lane) {
;     LAS float* scr = (LAS float*)(lds + wave * 8704);
;     unsigned char* ws = a->ws;
;     constexpr int I_TOTAL = (2048 / 64) * (2624 / 32) + (512 / 64) * (1536 / 32) + (512 / 64) * (2048 / 32) + 2 * (2048 / 64) * (2048 / 32) + (2048 / 64) * (4608 / 32)
;                           + 4 * (2048 / 64) * (DFF / 32) + 2 * (DFF / 64) * (2048 / 32);
;     for (int item = gw; item < I_TOTAL; item += NGW) {
;         int it = item;
;         if (conv_matrix(it, a->in[13], 2048, 2624, (bf16*)(ws + WS_WIN0), 0, scr, lane)) continue;
;         if (conv_matrix(it, a->in[19], 512, 1536, (bf16*)(ws + WS_WUQ), 0, scr, lane, 0.07216878364870322f * 1.4426950408889634f)) continue;
;         if (conv_matrix(it, a->in[20], 512, 2048, (bf16*)(ws + WS_WUKV), 0, scr, lane)) continue;
;         if (conv_matrix(it, a->in[14], 2048, 2048, (bf16*)(ws + WS_WOUT0), 0, scr, lane)) continue;
;         if (conv_matrix(it, a->in[21], 2048, 4608, (bf16*)(ws + WS_WIN1), 0, scr, lane)) continue;
;         if (conv_matrix(it, a->in[22], 2048, 2048, (bf16*)(ws + WS_WOUT1), 0, scr, lane)) continue;
;         if (conv_matrix(it, a->in[10], 2048, DFF, (bf16*)(ws + WS_WGU), 1, scr, lane)) continue;
;         if (conv_matrix(it, a->in[10] + (size_t)2048 * DFF, 2048, DFF, (bf16*)(ws + WS_WGU + 44 * MiB), 1, scr, lane)) continue;
;         if (conv_matrix(it, a->in[11], 2048, DFF, (bf16*)(ws + WS_WGU), 2, scr, lane)) continue;
;         if (conv_matrix(it, a->in[11] + (size_t)2048 * DFF, 2048, DFF, (bf16*)(ws + WS_WGU + 44 * MiB), 2, scr, lane)) continue;
;         if (conv_matrix(it, a->in[12], DFF, 2048, (bf16*)(ws + WS_WD), 0, scr, lane)) continue;
;         conv_matrix(it, a->in[12] + (size_t)2048 * DFF, DFF, 2048, (bf16*)(ws + WS_WD + 22 * MiB), 0, scr, lane);
;     }
.Ldfa_36:
	v_mbcnt_lo_u32_b32 v2, -1, 0
	v_mbcnt_hi_u32_b32 v2, -1, v2
	s_sub_i32 s5, s87, 88
	s_lshl_b32 s5, s5, 3
	s_add_i32 s5, s5, 0x0
	v_readlane_b32 s4, v254, 48
	s_nop 1
	v_add_u32_e32 v0, s4, v2
	s_movk_i32 s33, 0x540
	v_readfirstlane_b32 s4, v0
	s_ashr_i32 s6, s4, 6
	s_add_i32 s99, s6, s5
	s_mov_b64 s[4:5], s[0:1]
	s_cmp_gt_i32 s99, 0x29ff
	s_cbranch_scc1 .Ldfa_exit
	s_load_dwordx2 s[8:9], s[4:5], 0xf0
	v_bfe_u32 v0, v2, 5, 1
	v_and_b32_e32 v28, 31, v2
	v_bfe_u32 v1, v2, 3, 3
	v_lshlrev_b32_e32 v2, 3, v2
	v_and_b32_e32 v2, 56, v2
	v_mov_b32_e32 v3, 0
	v_mul_u32_u24_e32 v6, 0x84, v2
	v_lshlrev_b32_e32 v2, 1, v2
	s_mul_i32 s10, s6, 0x2200
	s_waitcnt lgkmcnt(0)
	v_lshl_add_u64 v[22:23], s[8:9], 0, v[2:3]
	s_mov_b64 s[6:7], 0x100000
	s_add_i32 s11, s10, 0
	v_lshl_add_u64 v[4:5], v[22:23], 0, s[6:7]
	v_lshlrev_b32_e32 v2, 2, v1
	s_mov_b64 s[6:7], 0xc00000
	v_add3_u32 v44, s11, v6, v2
	v_lshl_add_u64 v[6:7], v[22:23], 0, s[6:7]
	s_mov_b64 s[6:7], 0xe00000
	v_lshl_add_u64 v[8:9], v[22:23], 0, s[6:7]
	s_mov_b64 s[6:7], 0x1000000
	v_lshl_add_u64 v[10:11], v[22:23], 0, s[6:7]
	s_mov_b64 s[6:7], 0x1800000
	v_lshl_add_u64 v[12:13], v[22:23], 0, s[6:7]
	s_mov_b64 s[6:7], 0x2a00000
	v_lshl_add_u64 v[14:15], v[22:23], 0, s[6:7]
	s_mov_b64 s[6:7], 0x3200000
	v_lshl_add_u64 v[16:17], v[22:23], 0, s[6:7]
	s_mov_b64 s[6:7], 0x5e00000
	v_lshl_add_u64 v[18:19], v[22:23], 0, s[6:7]
	s_mov_b64 s[6:7], 0x8a00000
	v_mul_u32_u24_e32 v2, 0x84, v0
	v_lshl_add_u64 v[20:21], v[22:23], 0, s[6:7]
	s_mov_b64 s[6:7], 0xa000000
	v_or_b32_e32 v2, s10, v2
	v_lshlrev_b32_e32 v24, 2, v28
	v_or_b32_e32 v45, 8, v1
	v_or_b32_e32 v46, 16, v1
	v_or_b32_e32 v47, 24, v1
	v_lshl_add_u64 v[22:23], v[22:23], 0, s[6:7]
	v_add3_u32 v48, v2, v24, 0
	v_mov_b32_e32 v25, v3
	v_or_b32_e32 v49, 14, v0
	v_or_b32_e32 v50, 12, v0
	v_or_b32_e32 v51, 10, v0
	v_or_b32_e32 v52, 8, v0
	v_or_b32_e32 v53, 6, v0
	v_or_b32_e32 v54, 4, v0
	v_or_b32_e32 v55, 2, v0
	v_or_b32_e32 v26, 0x2c00000, v24
	v_mov_b32_e32 v27, v3
	s_movk_i32 s23, 0x2900
	s_movk_i32 s24, 0x7fff
	s_mov_b32 s25, 0xffff0000
	s_movk_i32 s26, 0x1800
	s_movk_i32 s27, 0x4800
	s_movk_i32 s28, 0x1600
	s_movk_i32 s29, 0x5800
	s_mov_b64 s[6:7], 0x2c00000
	v_lshlrev_b32_e32 v2, 2, v28
	v_mov_b32_e32 v56, 0x4800
	v_mov_b32_e32 v57, 0x5800
	s_branch .Ldfa_39
.Ldfa_38:
	s_add_i32 s99, s99, s33
	s_cmp_lt_i32 s99, 0x2a00
	s_cbranch_scc0 .Ldfa_exit

; #define LAS __attribute__((address_space(3)))
;     const int nblk = N / 32, items = (K / 64) * nblk;
;     if (it >= items) { it -= items; return false; }
;     const int kb = it / nblk, nb = it % nblk, n0 = 32 * nb;
;     const int drow0 = mode == 0 ? n0 : ((n0 >> 7) * 256 + (mode == 2 ? 128 : 0) + (n0 & 127));
;     transpose_item(W, K, N, WT, 64 * kb, n0, drow0, scr, lane, wsc);
;     return true;
; }
; __device__ __forceinline__ void p0_weights(KAP a, LAS unsigned char* lds, int gw, int NGW, int wave, int lane) {
;     LAS float* scr = (LAS float*)(lds + wave * 8704);
;     unsigned char* ws = a->ws;
;     constexpr int I_TOTAL = (2048 / 64) * (2624 / 32) + (512 / 64) * (1536 / 32) + (512 / 64) * (2048 / 32) + 2 * (2048 / 64) * (2048 / 32) + (2048 / 64) * (4608 / 32)
;                           + 4 * (2048 / 64) * (DFF / 32) + 2 * (DFF / 64) * (2048 / 32);
;     for (int item = gw; item < I_TOTAL; item += NGW) {
;         int it = item;
;         if (conv_matrix(it, a->in[13], 2048, 2624, (bf16*)(ws + WS_WIN0), 0, scr, lane)) continue;
;         if (conv_matrix(it, a->in[19], 512, 1536, (bf16*)(ws + WS_WUQ), 0, scr, lane, 0.07216878364870322f * 1.4426950408889634f)) continue;
;         if (conv_matrix(it, a->in[20], 512, 2048, (bf16*)(ws + WS_WUKV), 0, scr, lane)) continue;
;         if (conv_matrix(it, a->in[14], 2048, 2048, (bf16*)(ws + WS_WOUT0), 0, scr, lane)) continue;
;         if (conv_matrix(it, a->in[21], 2048, 4608, (bf16*)(ws + WS_WIN1), 0, scr, lane)) continue;
;         if (conv_matrix(it, a->in[22], 2048, 2048, (bf16*)(ws + WS_WOUT1), 0, scr, lane)) continue;
;         if (conv_matrix(it, a->in[10], 2048, DFF, (bf16*)(ws + WS_WGU), 1, scr, lane)) continue;
;         if (conv_matrix(it, a->in[10] + (size_t)2048 * DFF, 2048, DFF, (bf16*)(ws + WS_WGU + 44 * MiB), 1, scr, lane)) continue;
;         if (conv_matrix(it, a->in[11], 2048, DFF, (bf16*)(ws + WS_WGU), 2, scr, lane)) continue;
;         if (conv_matrix(it, a->in[11] + (size_t)2048 * DFF, 2048, DFF, (bf16*)(ws + WS_WGU + 44 * MiB), 2, scr, lane)) continue;
;         if (conv_matrix(it, a->in[12], DFF, 2048, (bf16*)(ws + WS_WD), 0, scr, lane)) continue;
;         conv_matrix(it, a->in[12] + (size_t)2048 * DFF, DFF, 2048, (bf16*)(ws + WS_WD + 22 * MiB), 0, scr, lane);
;     }
.Ldfb_36:
	v_mbcnt_lo_u32_b32 v2, -1, 0
	v_mbcnt_hi_u32_b32 v2, -1, v2
	s_sub_i32 s5, s87, 64
	s_lshl_b32 s5, s5, 3
	s_add_i32 s5, s5, 0x2a00
	v_readlane_b32 s4, v254, 48
	s_nop 1
	v_add_u32_e32 v0, s4, v2
	s_movk_i32 s33, 0x600
	v_readfirstlane_b32 s4, v0
	s_ashr_i32 s6, s4, 6
	s_add_i32 s99, s6, s5
	s_mov_b64 s[4:5], s[0:1]
	s_cmp_gt_i32 s99, 0x41ff
	s_cbranch_scc1 .Ldfb_exit
	s_load_dwordx2 s[8:9], s[4:5], 0xf0
	v_bfe_u32 v0, v2, 5, 1
	v_and_b32_e32 v28, 31, v2
	v_bfe_u32 v1, v2, 3, 3
	v_lshlrev_b32_e32 v2, 3, v2
	v_and_b32_e32 v2, 56, v2
	v_mov_b32_e32 v3, 0
	v_mul_u32_u24_e32 v6, 0x84, v2
	v_lshlrev_b32_e32 v2, 1, v2
	s_mul_i32 s10, s6, 0x2200
	s_waitcnt lgkmcnt(0)
	v_lshl_add_u64 v[22:23], s[8:9], 0, v[2:3]
	s_mov_b64 s[6:7], 0x100000
	s_add_i32 s11, s10, 0
	v_lshl_add_u64 v[4:5], v[22:23], 0, s[6:7]
	v_lshlrev_b32_e32 v2, 2, v1
	s_mov_b64 s[6:7], 0xc00000
	v_add3_u32 v44, s11, v6, v2
	v_lshl_add_u64 v[6:7], v[22:23], 0, s[6:7]
	s_mov_b64 s[6:7], 0xe00000
	v_lshl_add_u64 v[8:9], v[22:23], 0, s[6:7]
	s_mov_b64 s[6:7], 0x1000000
	v_lshl_add_u64 v[10:11], v[22:23], 0, s[6:7]
	s_mov_b64 s[6:7], 0x1800000
	v_lshl_add_u64 v[12:13], v[22:23], 0, s[6:7]
	s_mov_b64 s[6:7], 0x2a00000
	v_lshl_add_u64 v[14:15], v[22:23], 0, s[6:7]
	s_mov_b64 s[6:7], 0x3200000
	v_lshl_add_u64 v[16:17], v[22:23], 0, s[6:7]
	s_mov_b64 s[6:7], 0x5e00000
	v_lshl_add_u64 v[18:19], v[22:23], 0, s[6:7]
	s_mov_b64 s[6:7], 0x8a00000
	v_mul_u32_u24_e32 v2, 0x84, v0
	v_lshl_add_u64 v[20:21], v[22:23], 0, s[6:7]
	s_mov_b64 s[6:7], 0xa000000
	v_or_b32_e32 v2, s10, v2
	v_lshlrev_b32_e32 v24, 2, v28
	v_or_b32_e32 v45, 8, v1
	v_or_b32_e32 v46, 16, v1
	v_or_b32_e32 v47, 24, v1
	v_lshl_add_u64 v[22:23], v[22:23], 0, s[6:7]
	v_add3_u32 v48, v2, v24, 0
	v_mov_b32_e32 v25, v3
	v_or_b32_e32 v49, 14, v0
	v_or_b32_e32 v50, 12, v0
	v_or_b32_e32 v51, 10, v0
	v_or_b32_e32 v52, 8, v0
	v_or_b32_e32 v53, 6, v0
	v_or_b32_e32 v54, 4, v0
	v_or_b32_e32 v55, 2, v0
	v_or_b32_e32 v26, 0x2c00000, v24
	v_mov_b32_e32 v27, v3
	s_movk_i32 s23, 0x2900
	s_movk_i32 s24, 0x7fff
	s_mov_b32 s25, 0xffff0000
	s_movk_i32 s26, 0x1800
	s_movk_i32 s27, 0x4800
	s_movk_i32 s28, 0x1600
	s_movk_i32 s29, 0x5800
	s_mov_b64 s[6:7], 0x2c00000
	v_lshlrev_b32_e32 v2, 2, v28
	v_mov_b32_e32 v56, 0x4800
	v_mov_b32_e32 v57, 0x5800
	s_branch .Ldfb_39
